# P5: CUs 64-255 (no sample unit) start ~12us later so CUs 0-63 run their HBM-bound epilogues alone
# baseline (speedup 1.0000x reference)
; __global__ void __launch_bounds__(512, 2) fwd_megakernel(Args a) {
;     ...
;     {
;         pg8::Gemm g{U + C_ZP, (const bf16_t*)(a.ws + WS_WOUT), MP, 1024, 2048, LDU, 2048, 0};
;         pg8::PanelOrder S{bid};
;         pg8::EpiResLN E{a.in[0], (const float*)(a.ws + WS_GATEF), a.in[18], a.out, (float*)(a.ws + WS_XBUF), (unsigned*)(a.ws + WS_CTL) + 4096};
;         pg8::gemm_phase<pg8::EpiResLN, pg8::PanelOrder, true, true>(L, g, S, E);
;         pg8::Gemm g2{U + C_ZP, (const bf16_t*)(a.ws + WS_WOUT), MT, 1024, 512, LDU, 2048, 0};
;         pg8::SampleOrder S2{bid};
;         pg8::EpiPart E2{(float*)(a.ws + WS_PART)};
;         pg8::gemm_phase<pg8::EpiPart, pg8::SampleOrder, true, true>(L, g2, S2, E2);
.LBB0_1206:
	s_or_b64 exec, exec, s[0:1]
	v_mov_b32_e32 v9, v180
	s_waitcnt lgkmcnt(0)
	s_barrier
	s_cmp_lt_u32 s2, 64
	s_cbranch_scc1 .Lp5_nostagger
	s_sleep 127
	s_sleep 127
	s_sleep 127
